# PEER pass-B LN2 epilogue: gamma/beta pieces loaded up front, four stores back to back; pass-A header loads issued together
# baseline (speedup 1.0000x reference)
.LpA_hdr:
	v_ashrrev_i32_e32 v143, 31, v142
	v_lshlrev_b64 v[164:165], 11, v[142:143]
	v_lshl_add_u64 v[162:163], v[144:145], 0, v[164:165]
	global_load_dwordx4 v[2:5], v[162:163], off
	global_load_dwordx4 v[6:9], v[162:163], off offset:16
	v_lshlrev_b64 v[10:11], 9, v[142:143]
	v_lshl_or_b32 v10, v136, 2, v10
	v_lshl_add_u64 v[18:19], s[82:83], 0, v[10:11]
	v_lshl_add_u64 v[20:21], s[64:65], 0, v[10:11]
	global_load_dword v211, v[18:19], off
	global_load_dword v212, v[18:19], off offset:256
	global_load_dword v213, v[20:21], off
	global_load_dword v214, v[20:21], off offset:256
	s_mov_b32 s33, 0
	s_mov_b32 s34, 0
	v_mov_b32_e32 v180, 0
	v_mov_b32_e32 v181, v139
	v_mov_b32_e32 v178, 0
	v_mov_b32_e32 v179, v139
	v_mov_b32_e32 v176, 0
	v_mov_b32_e32 v177, v139
	v_mov_b32_e32 v174, 0
	v_mov_b32_e32 v175, v139
	v_mov_b32_e32 v172, 0
	v_mov_b32_e32 v173, v139
	v_mov_b32_e32 v170, 0
	v_mov_b32_e32 v171, v139
	v_mov_b32_e32 v168, 0
	v_mov_b32_e32 v169, v139
	v_mov_b32_e32 v166, 0
	v_mov_b32_e32 v167, v139
	s_waitcnt vmcnt(5)
	v_lshlrev_b32_e32 v10, 16, v2
	v_and_b32_e32 v11, 0xffff0000, v2
	v_lshlrev_b32_e32 v12, 16, v3
	v_and_b32_e32 v13, 0xffff0000, v3
	v_lshlrev_b32_e32 v2, 16, v4
	v_and_b32_e32 v3, 0xffff0000, v4
	v_lshlrev_b32_e32 v4, 16, v5
	v_and_b32_e32 v5, 0xffff0000, v5
	s_waitcnt vmcnt(4)
	v_lshlrev_b32_e32 v14, 16, v6
	v_and_b32_e32 v15, 0xffff0000, v6
	v_lshlrev_b32_e32 v16, 16, v7
	v_and_b32_e32 v17, 0xffff0000, v7
	v_lshlrev_b32_e32 v6, 16, v8
	v_and_b32_e32 v7, 0xffff0000, v8
	v_lshlrev_b32_e32 v8, 16, v9
	v_and_b32_e32 v9, 0xffff0000, v9
	ds_write_b128 v201, v[10:13]
	ds_write_b128 v201, v[2:5] offset:16
	ds_write_b128 v201, v[14:17] offset:32
	ds_write_b128 v201, v[6:9] offset:48
	s_nop 0
	s_nop 0
	s_nop 0
	s_nop 0
	v_and_b32_e32 v3, 64, v182
	ds_read_b32 v232, v137
	ds_read_b32 v233, v183
	ds_read_b32 v234, v184
	ds_read_b32 v235, v185
	ds_read_b32 v236, v186
	ds_read_b32 v237, v187
	ds_read_b32 v238, v188
	ds_read_b32 v239, v189
	ds_read_b32 v240, v190
	ds_read_b32 v241, v191
	ds_read_b32 v242, v192
	ds_read_b32 v243, v193
	ds_read_b32 v244, v194
	ds_read_b32 v245, v195
	ds_read_b32 v246, v196
	ds_read_b32 v247, v197
	v_xor_b32_e32 v2, 1, v182
	v_add_u32_e32 v4, 64, v3
	v_cmp_lt_i32_e64 s[2:3], v2, v4
	v_or_b32_e32 v231, v198, v3
	s_nop 0
	v_cndmask_b32_e64 v2, v182, v2, s[2:3]
	v_lshlrev_b32_e32 v205, 2, v2
	v_xor_b32_e32 v2, 2, v182
	v_cmp_lt_i32_e64 s[2:3], v2, v4
	s_nop 1
	v_cndmask_b32_e64 v2, v182, v2, s[2:3]
	v_lshlrev_b32_e32 v206, 2, v2
	v_xor_b32_e32 v2, 4, v182
	v_cmp_lt_i32_e64 s[2:3], v2, v4
	s_nop 1
	v_cndmask_b32_e64 v2, v182, v2, s[2:3]
	v_lshlrev_b32_e32 v207, 2, v2
	v_xor_b32_e32 v2, 8, v182
	v_cmp_lt_i32_e64 s[2:3], v2, v4
	s_nop 1
	v_cndmask_b32_e64 v2, v182, v2, s[2:3]
	v_lshlrev_b32_e32 v208, 2, v2
	v_xor_b32_e32 v2, 16, v182
	v_cmp_lt_i32_e64 s[2:3], v2, v4
	s_nop 1
	v_cndmask_b32_e64 v2, v182, v2, s[2:3]
	v_lshlrev_b32_e32 v209, 2, v2
	v_xor_b32_e32 v2, 32, v182
	v_cmp_lt_i32_e64 s[2:3], v2, v4
	s_nop 1
	v_cndmask_b32_e64 v2, v182, v2, s[2:3]
	v_lshlrev_b32_e32 v210, 2, v2
	s_waitcnt vmcnt(0)
	s_add_i32 s49, s33, 0
	v_readlane_b32 s40, v211, s49
	s_add_i32 s49, s33, 1
	v_readlane_b32 s41, v211, s49
	s_add_i32 s49, s33, 2
	v_readlane_b32 s42, v211, s49
	s_add_i32 s49, s33, 3
	v_readlane_b32 s43, v211, s49
	s_add_i32 s49, s33, 4
	v_readlane_b32 s44, v211, s49
	s_add_i32 s49, s33, 5
	v_readlane_b32 s45, v211, s49
	s_add_i32 s49, s33, 6
	v_readlane_b32 s46, v211, s49
	s_add_i32 s49, s33, 7
	v_readlane_b32 s47, v211, s49
	v_mad_u32_u24 v152, s40, v202, v138
	global_load_dwordx3 v[48:50], v152, s[78:79]
	v_mad_u32_u24 v153, s41, v202, v138
	global_load_dwordx3 v[92:94], v153, s[78:79]
	v_mad_u32_u24 v154, s42, v202, v138
	global_load_dwordx3 v[54:56], v154, s[78:79]
	v_mad_u32_u24 v155, s43, v202, v138
	global_load_dwordx3 v[80:82], v155, s[78:79]
	v_mad_u32_u24 v152, s44, v202, v138
	global_load_dwordx3 v[60:62], v152, s[78:79]
	v_mad_u32_u24 v153, s45, v202, v138
	global_load_dwordx3 v[84:86], v153, s[78:79]
	v_mad_u32_u24 v154, s46, v202, v138
	global_load_dwordx3 v[76:78], v154, s[78:79]
	v_mad_u32_u24 v155, s47, v202, v138
	global_load_dwordx3 v[88:90], v155, s[78:79]
	s_add_i32 s49, s33, 8
	v_readlane_b32 s40, v211, s49
	s_add_i32 s49, s33, 9
	v_readlane_b32 s41, v211, s49
	s_add_i32 s49, s33, 10
	v_readlane_b32 s42, v211, s49
	s_add_i32 s49, s33, 11
	v_readlane_b32 s43, v211, s49
	s_add_i32 s49, s33, 12
	v_readlane_b32 s44, v211, s49
	s_add_i32 s49, s33, 13
	v_readlane_b32 s45, v211, s49
	s_add_i32 s49, s33, 14
	v_readlane_b32 s46, v211, s49
	s_add_i32 s49, s33, 15
	v_readlane_b32 s47, v211, s49
	v_mad_u32_u24 v152, s40, v202, v138
	global_load_dwordx3 v[34:36], v152, s[78:79]
	v_mad_u32_u24 v153, s41, v202, v138
	global_load_dwordx3 v[44:46], v153, s[78:79]
	v_mad_u32_u24 v154, s42, v202, v138
	global_load_dwordx3 v[66:68], v154, s[78:79]
	v_mad_u32_u24 v155, s43, v202, v138
	global_load_dwordx3 v[40:42], v155, s[78:79]
	v_mad_u32_u24 v152, s44, v202, v138
	global_load_dwordx3 v[98:100], v152, s[78:79]
	v_mad_u32_u24 v153, s45, v202, v138
	global_load_dwordx3 v[72:74], v153, s[78:79]
	v_mad_u32_u24 v154, s46, v202, v138
	global_load_dwordx3 v[130:132], v154, s[78:79]
	v_mad_u32_u24 v155, s47, v202, v138
	global_load_dwordx3 v[104:106], v155, s[78:79]

.LpB_epi:
	global_load_dwordx4 v[50:53], v[156:157], off
	global_load_dwordx4 v[54:57], v[158:159], off
	global_load_dwordx4 v[58:61], v[156:157], off offset:16
	global_load_dwordx4 v[62:65], v[158:159], off offset:16
	global_load_dwordx4 v[66:69], v[156:157], off offset:32
	global_load_dwordx4 v[70:73], v[158:159], off offset:32
	global_load_dwordx4 v[74:77], v[156:157], off offset:48
	global_load_dwordx4 v[78:81], v[158:159], off offset:48
	ds_write_b32 v137, v178
	ds_write_b32 v183, v179
	ds_write_b32 v184, v176
	ds_write_b32 v185, v177
	ds_write_b32 v186, v174
	ds_write_b32 v187, v175
	ds_write_b32 v188, v172
	ds_write_b32 v189, v173
	ds_write_b32 v190, v170
	ds_write_b32 v191, v171
	ds_write_b32 v192, v168
	ds_write_b32 v193, v169
	ds_write_b32 v194, v166
	ds_write_b32 v195, v167
	ds_write_b32 v196, v180
	ds_write_b32 v197, v181
	v_lshl_add_u64 v[18:19], v[146:147], 0, v[164:165]
	global_load_dwordx4 v[2:5], v[18:19], off
	global_load_dwordx4 v[6:9], v[162:163], off
	global_load_dwordx4 v[10:13], v[18:19], off offset:16
	global_load_dwordx4 v[14:17], v[162:163], off offset:16
	ds_read_b128 v[18:21], v201
	ds_read_b128 v[22:25], v201 offset:16
	ds_read_b128 v[26:29], v201 offset:32
	ds_read_b128 v[30:33], v201 offset:48
	s_waitcnt vmcnt(3)
	v_lshlrev_b32_e32 v34, 16, v2
	s_waitcnt vmcnt(2)
	v_lshlrev_b32_e32 v36, 16, v6
	v_and_b32_e32 v37, 0xffff0000, v6
	v_lshlrev_b32_e32 v6, 16, v7
	v_and_b32_e32 v7, 0xffff0000, v7
	v_lshlrev_b32_e32 v40, 16, v8
	v_and_b32_e32 v41, 0xffff0000, v8
	v_lshlrev_b32_e32 v8, 16, v9
	v_and_b32_e32 v9, 0xffff0000, v9
	v_and_b32_e32 v35, 0xffff0000, v2
	v_lshlrev_b32_e32 v2, 16, v3
	v_and_b32_e32 v3, 0xffff0000, v3
	v_lshlrev_b32_e32 v38, 16, v4
	v_and_b32_e32 v39, 0xffff0000, v4
	v_lshlrev_b32_e32 v4, 16, v5
	v_and_b32_e32 v5, 0xffff0000, v5
	s_waitcnt vmcnt(0)
	v_lshlrev_b32_e32 v44, 16, v14
	v_and_b32_e32 v45, 0xffff0000, v14
	v_lshlrev_b32_e32 v14, 16, v15
	v_and_b32_e32 v15, 0xffff0000, v15
	s_waitcnt lgkmcnt(3)
	v_pk_fma_f32 v[18:19], v[36:37], s[12:13], v[18:19] op_sel_hi:[1,0,1]
	v_pk_fma_f32 v[6:7], v[6:7], s[12:13], v[20:21] op_sel_hi:[1,0,1]
	s_waitcnt lgkmcnt(2)
	v_pk_fma_f32 v[20:21], v[40:41], s[12:13], v[22:23] op_sel_hi:[1,0,1]
	v_pk_fma_f32 v[8:9], v[8:9], s[12:13], v[24:25] op_sel_hi:[1,0,1]
	s_waitcnt lgkmcnt(1)
	v_pk_fma_f32 v[22:23], v[44:45], s[12:13], v[26:27] op_sel_hi:[1,0,1]
	v_pk_fma_f32 v[14:15], v[14:15], s[12:13], v[28:29] op_sel_hi:[1,0,1]
	v_pk_add_f32 v[18:19], v[18:19], v[34:35]
	v_pk_add_f32 v[26:27], v[6:7], v[2:3]
	v_pk_add_f32 v[20:21], v[20:21], v[38:39]
	v_pk_add_f32 v[28:29], v[8:9], v[4:5]
	v_lshlrev_b32_e32 v42, 16, v10
	v_and_b32_e32 v43, 0xffff0000, v10
	v_lshlrev_b32_e32 v10, 16, v11
	v_and_b32_e32 v11, 0xffff0000, v11
	v_lshlrev_b32_e32 v48, 16, v16
	v_and_b32_e32 v49, 0xffff0000, v16
	v_lshlrev_b32_e32 v16, 16, v17
	v_and_b32_e32 v17, 0xffff0000, v17
	v_mov_b32_e32 v2, v18
	v_mov_b32_e32 v3, v27
	v_pk_mov_b32 v[4:5], v[18:19], v[26:27] op_sel:[1,0]
	v_mov_b32_e32 v6, v20
	v_mov_b32_e32 v7, v29
	v_pk_mov_b32 v[8:9], v[20:21], v[28:29] op_sel:[1,0]
	v_lshlrev_b32_e32 v46, 16, v12
	v_and_b32_e32 v47, 0xffff0000, v12
	v_lshlrev_b32_e32 v12, 16, v13
	v_and_b32_e32 v13, 0xffff0000, v13
	s_waitcnt lgkmcnt(0)
	v_pk_fma_f32 v[24:25], v[48:49], s[12:13], v[30:31] op_sel_hi:[1,0,1]
	v_pk_fma_f32 v[16:17], v[16:17], s[12:13], v[32:33] op_sel_hi:[1,0,1]
	v_pk_add_f32 v[22:23], v[22:23], v[42:43]
	v_pk_add_f32 v[10:11], v[14:15], v[10:11]
	v_pk_add_f32 v[2:3], v[2:3], v[4:5]
	v_pk_add_f32 v[4:5], v[6:7], v[8:9]
	v_pk_add_f32 v[14:15], v[24:25], v[46:47]
	v_pk_add_f32 v[12:13], v[16:17], v[12:13]
	v_pk_add_f32 v[16:17], v[22:23], v[22:23] op_sel:[0,1] op_sel_hi:[1,0]
	v_pk_add_f32 v[24:25], v[10:11], v[10:11] op_sel:[1,0] op_sel_hi:[0,1]
	v_add_f32_e32 v6, v2, v3
	v_pk_add_f32 v[2:3], v[4:5], v[4:5] op_sel:[0,1] op_sel_hi:[1,0]
	v_mov_b32_e32 v31, v14
	v_add_f32_e32 v30, 0, v6
	v_mov_b32_e32 v3, v15
	v_mov_b32_e32 v17, v13
	v_mov_b32_e32 v25, v12
	v_pk_add_f32 v[2:3], v[30:31], v[2:3]
	v_pk_add_f32 v[4:5], v[16:17], v[24:25]
	s_nop 0
	v_pk_add_f32 v[2:3], v[2:3], v[4:5]
	s_nop 0
	v_add_f32_e32 v2, v2, v3
	s_nop 1
	v_add_f32_dpp v2, v2, v2 quad_perm:[1,0,3,2] row_mask:0xf bank_mask:0xf bound_ctrl:1
	s_nop 1
	v_add_f32_dpp v2, v2, v2 quad_perm:[2,3,0,1] row_mask:0xf bank_mask:0xf bound_ctrl:1
	s_nop 1
	v_add_f32_dpp v2, v2, v2 row_half_mirror row_mask:0xf bank_mask:0xf bound_ctrl:1
	s_nop 1
	v_add_f32_dpp v2, v2, v2 row_mirror row_mask:0xf bank_mask:0xf bound_ctrl:1
	s_nop 1
	v_add_f32_dpp v2, v2, v2 row_bcast:15 row_mask:0xa bank_mask:0xf
	s_nop 1
	v_add_f32_dpp v2, v2, v2 row_bcast:31 row_mask:0xc bank_mask:0xf
	s_nop 1
	v_readlane_b32 s53, v2, 63
	s_nop 0
	s_nop 0
	v_mov_b32_e32 v16, s53
	v_mul_f32_e32 v16, 0x3a800000, v16
	v_pk_add_f32 v[18:19], v[18:19], v[16:17] op_sel_hi:[1,0] neg_lo:[0,1] neg_hi:[0,1]
	v_pk_add_f32 v[24:25], v[26:27], v[16:17] op_sel_hi:[1,0] neg_lo:[0,1] neg_hi:[0,1]
	v_pk_add_f32 v[20:21], v[20:21], v[16:17] op_sel_hi:[1,0] neg_lo:[0,1] neg_hi:[0,1]
	v_pk_add_f32 v[26:27], v[28:29], v[16:17] op_sel_hi:[1,0] neg_lo:[0,1] neg_hi:[0,1]
	v_pk_add_f32 v[22:23], v[22:23], v[16:17] op_sel_hi:[1,0] neg_lo:[0,1] neg_hi:[0,1]
	v_pk_add_f32 v[10:11], v[10:11], v[16:17] op_sel_hi:[1,0] neg_lo:[0,1] neg_hi:[0,1]
	v_pk_add_f32 v[14:15], v[14:15], v[16:17] op_sel_hi:[1,0] neg_lo:[0,1] neg_hi:[0,1]
	v_pk_add_f32 v[12:13], v[12:13], v[16:17] op_sel_hi:[1,0] neg_lo:[0,1] neg_hi:[0,1]
	v_pk_mul_f32 v[16:17], v[18:19], v[18:19]
	v_pk_mul_f32 v[28:29], v[24:25], v[24:25]
	v_add_f32_e32 v16, v16, v17
	v_add_f32_e32 v16, v28, v16
	v_pk_mul_f32 v[30:31], v[20:21], v[20:21]
	v_add_f32_e32 v16, v29, v16
	v_add_f32_e32 v16, v30, v16
	v_pk_mul_f32 v[32:33], v[26:27], v[26:27]
	v_add_f32_e32 v16, v31, v16
	v_add_f32_e32 v16, v32, v16
	v_pk_mul_f32 v[34:35], v[22:23], v[22:23]
	v_add_f32_e32 v16, v33, v16
	v_add_f32_e32 v16, v34, v16
	v_pk_mul_f32 v[36:37], v[10:11], v[10:11]
	v_add_f32_e32 v16, v35, v16
	v_add_f32_e32 v16, v36, v16
	v_pk_mul_f32 v[38:39], v[14:15], v[14:15]
	v_add_f32_e32 v16, v37, v16
	v_add_f32_e32 v16, v38, v16
	v_pk_mul_f32 v[40:41], v[12:13], v[12:13]
	v_add_f32_e32 v16, v39, v16
	v_add_f32_e32 v16, v40, v16
	v_add_f32_e32 v16, v41, v16
	s_nop 1
	v_add_f32_dpp v16, v16, v16 quad_perm:[1,0,3,2] row_mask:0xf bank_mask:0xf bound_ctrl:1
	s_nop 1
	v_add_f32_dpp v16, v16, v16 quad_perm:[2,3,0,1] row_mask:0xf bank_mask:0xf bound_ctrl:1
	s_nop 1
	v_add_f32_dpp v16, v16, v16 row_half_mirror row_mask:0xf bank_mask:0xf bound_ctrl:1
	s_nop 1
	v_add_f32_dpp v16, v16, v16 row_mirror row_mask:0xf bank_mask:0xf bound_ctrl:1
	s_nop 1
	v_add_f32_dpp v16, v16, v16 row_bcast:15 row_mask:0xa bank_mask:0xf
	s_nop 1
	v_add_f32_dpp v16, v16, v16 row_bcast:31 row_mask:0xc bank_mask:0xf
	s_nop 1
	v_readlane_b32 s53, v16, 63
	s_nop 3
	v_mov_b32_e32 v16, s53
	v_fmamk_f32 v16, v16, 0x3a800000, v149
	v_mul_f32_e32 v17, 0x4b800000, v16
	v_cmp_gt_f32_e64 s[2:3], s30, v16
	s_nop 1
	v_cndmask_b32_e64 v16, v16, v17, s[2:3]
	v_rsq_f32_e32 v28, v16
	v_lshlrev_b64 v[16:17], 12, v[142:143]
	v_lshl_add_u64 v[16:17], v[160:161], 0, v[16:17]
	v_add_u32_e32 v142, s6, v142
	v_mul_f32_e32 v29, 0x45800000, v28
	v_cndmask_b32_e64 v28, v28, v29, s[2:3]
	v_pk_mul_f32 v[18:19], v[18:19], v[28:29] op_sel_hi:[1,0]
	v_pk_mul_f32 v[24:25], v[24:25], v[28:29] op_sel_hi:[1,0]
	v_pk_fma_f32 v[82:83], v[50:51], v[18:19], v[54:55]
	v_pk_fma_f32 v[84:85], v[52:53], v[24:25], v[56:57]
	global_store_dwordx4 v[16:17], v[82:85], off
	v_pk_mul_f32 v[18:19], v[20:21], v[28:29] op_sel_hi:[1,0]
	v_pk_mul_f32 v[20:21], v[26:27], v[28:29] op_sel_hi:[1,0]
	v_pk_mul_f32 v[10:11], v[10:11], v[28:29] op_sel_hi:[1,0]
	v_cmp_lt_i32_e64 s[2:3], s31, v142
	v_pk_mul_f32 v[12:13], v[12:13], v[28:29] op_sel_hi:[1,0]
	s_or_b64 s[10:11], s[2:3], s[10:11]
	v_pk_fma_f32 v[86:87], v[58:59], v[18:19], v[62:63]
	v_pk_fma_f32 v[88:89], v[60:61], v[20:21], v[64:65]
	global_store_dwordx4 v[16:17], v[86:89], off offset:16
	v_pk_mul_f32 v[18:19], v[22:23], v[28:29] op_sel_hi:[1,0]
	v_pk_fma_f32 v[92:93], v[68:69], v[10:11], v[72:73]
	v_pk_fma_f32 v[90:91], v[66:67], v[18:19], v[70:71]
	global_store_dwordx4 v[16:17], v[90:93], off offset:32
	v_pk_mul_f32 v[10:11], v[14:15], v[28:29] op_sel_hi:[1,0]
	v_pk_fma_f32 v[96:97], v[12:13], v[76:77], v[80:81]
	v_pk_fma_f32 v[94:95], v[10:11], v[74:75], v[78:79]
	global_store_dwordx4 v[16:17], v[94:97], off offset:48
	s_andn2_b64 exec, exec, s[10:11]
	s_cbranch_execz .LBB0_3658
